# v12 variant: PV-phase VALU budget 5 per MFMA gap so the softmax-start stream finishes inside the PV MFMAs
# speedup vs baseline: 1.0054x; 1.0054x over previous
; __device__ __forceinline__ void finishSM(f32x16& p0, f32x16& p1, float alpha, float& l_reg, bf16x8& pa0, bf16x8& pa1, bf16x8& pa2, bf16x8& pa3) {
; #pragma unroll
;   for (int r = 0; r < 16; ++r) p1[r] = __builtin_amdgcn_exp2f(p1[r]);
;   float ps = 0;
; #pragma unroll
;   for (int r = 0; r < 16; ++r) ps += p0[r];
; #pragma unroll
;   for (int r = 0; r < 16; ++r) ps += p1[r];
;   { auto rr = __builtin_amdgcn_permlane32_swap(__float_as_uint(ps), __float_as_uint(ps), false, false);
;     ps = __uint_as_float(rr[0]) + __uint_as_float(rr[1]); }
;   l_reg = l_reg * alpha + ps;
;     ...
;   PK4(p0, 0, pa0); PK4(p0, 8, pa1); PK4(p1, 0, pa2); PK4(p1, 8, pa3);
;     ...
; }
; __device__ __forceinline__ void qkt(f32x16& p0, f32x16& p1, const char* Ks, const bf16x8* qr, const char* qrl, int r32, int hi) {
;   p0 = f32x16{}; p1 = f32x16{};
; #pragma unroll
;   for (int d0 = 0; d0 < 8; ++d0) { int cb = (d0 * 16 + hi * 8) * 2;
;     bf16x8 b0 = *reinterpret_cast<const bf16x8*>(Ks + KSWZ(r32, cb));
;     bf16x8 b1 = *reinterpret_cast<const bf16x8*>(Ks + KSWZ(32 + r32, cb));
;     p0 = __builtin_amdgcn_mfma_f32_32x32x16_bf16(b0, qr[d0], p0, 0, 0, 0);
;     p1 = __builtin_amdgcn_mfma_f32_32x32x16_bf16(b1, qr[d0], p1, 0, 0, 0); }
; #pragma unroll
;   for (int d0 = 8; d0 < 12; ++d0) { int cb = (d0 * 16 + hi * 8) * 2;
;     bf16x8 b0 = *reinterpret_cast<const bf16x8*>(Ks + KSWZ(r32, cb));
;     bf16x8 b1 = *reinterpret_cast<const bf16x8*>(Ks + KSWZ(32 + r32, cb));
;     bf16x8 qf = *reinterpret_cast<const bf16x8*>(qrl + (((2 * (d0 - 8) + hi) ^ ((r32 >> 1) & 7)) << 4));
;     p0 = __builtin_amdgcn_mfma_f32_32x32x16_bf16(b0, qf, p0, 0, 0, 0);
;     p1 = __builtin_amdgcn_mfma_f32_32x32x16_bf16(b1, qf, p1, 0, 0, 0); }
; }
.LBB0_1151:
	s_sub_i32 s30, s76, 1
	s_cmp_eq_u32 s76, 0
	s_cselect_b32 s30, 2, s30
	s_add_i32 s18, s76, 1
	s_cmp_lg_u32 s76, 2
	s_cselect_b32 s18, s18, 0
	ds_read_b128 v[232:235], v199 offset:36864
	ds_read_b128 v[236:239], v199 offset:49152
	ds_read_b128 v[240:243], v205 offset:36864
	ds_read_b128 v[248:251], v205 offset:49152
	ds_read_b128 v[244:247], v206 offset:36864
	v_exp_f32_e32 v162, v162
	v_add_f32_e32 v211, v225, v228
	v_exp_f32_e32 v163, v163
	v_add_f32_e32 v211, v226, v211
	v_exp_f32_e32 v160, v160
	s_waitcnt lgkmcnt(3)
	v_mfma_f32_32x32x16_bf16 v[80:95], v[232:235], v[124:127], 0
	ds_read_b128 v[232:235], v206 offset:49152
	v_add_f32_e32 v211, v229, v211
	v_exp_f32_e32 v161, v161
	v_add_f32_e32 v211, v227, v211
	v_exp_f32_e32 v158, v158
	v_mfma_f32_32x32x16_bf16 v[64:79], v[236:239], v[124:127], 0
	ds_read_b128 v[236:239], v208 offset:36864
	v_add_f32_e32 v211, v230, v211
	v_exp_f32_e32 v159, v159
	v_add_f32_e32 v211, v223, v211
	v_exp_f32_e32 v156, v156
	s_waitcnt lgkmcnt(3)
	v_mfma_f32_32x32x16_bf16 v[80:95], v[240:243], v[120:123], v[80:95]
	ds_read_b128 v[240:243], v208 offset:49152
	v_add_f32_e32 v211, v224, v211
	v_exp_f32_e32 v157, v157
	v_add_f32_e32 v211, v219, v211
	v_exp_f32_e32 v154, v154
	v_mfma_f32_32x32x16_bf16 v[64:79], v[248:251], v[120:123], v[64:79]
	ds_read_b128 v[248:251], v207 offset:36864
	v_add_f32_e32 v211, v221, v211
	v_exp_f32_e32 v155, v155
	v_add_f32_e32 v211, v220, v211
	v_exp_f32_e32 v152, v152
	s_waitcnt lgkmcnt(3)
	v_mfma_f32_32x32x16_bf16 v[80:95], v[244:247], v[116:119], v[80:95]
	ds_read_b128 v[244:247], v207 offset:49152
	v_add_f32_e32 v211, v222, v211
	v_exp_f32_e32 v153, v153
	v_add_f32_e32 v211, v215, v211
	v_exp_f32_e32 v150, v150
	v_mfma_f32_32x32x16_bf16 v[64:79], v[232:235], v[116:119], v[64:79]
	ds_read_b128 v[232:235], v204 offset:36864
	v_add_f32_e32 v211, v217, v211
	v_exp_f32_e32 v151, v151
	v_add_f32_e32 v211, v216, v211
	v_exp_f32_e32 v148, v148
	s_waitcnt lgkmcnt(3)
	v_mfma_f32_32x32x16_bf16 v[80:95], v[236:239], v[112:115], v[80:95]
	ds_read_b128 v[236:239], v204 offset:49152
	v_add_f32_e32 v211, v218, v211
	v_exp_f32_e32 v149, v149
	v_add_f32_e32 v212, v162, v163
	v_add_f32_e32 v212, v160, v212
	v_add_f32_e32 v212, v161, v212
	v_mfma_f32_32x32x16_bf16 v[64:79], v[240:243], v[112:115], v[64:79]
	ds_read_b128 v[240:243], v203 offset:36864
	v_add_f32_e32 v212, v158, v212
	v_add_f32_e32 v212, v159, v212
	v_add_f32_e32 v212, v156, v212
	v_add_f32_e32 v212, v157, v212
	v_add_f32_e32 v212, v154, v212
	v_add_f32_e32 v212, v155, v212
	s_waitcnt lgkmcnt(3)
	v_mfma_f32_32x32x16_bf16 v[80:95], v[248:251], v[108:111], v[80:95]
	ds_read_b128 v[248:251], v203 offset:49152
	v_add_f32_e32 v212, v152, v212
	v_add_f32_e32 v212, v153, v212
	v_add_f32_e32 v212, v150, v212
	v_add_f32_e32 v212, v151, v212
	v_add_f32_e32 v212, v148, v212
	v_add_f32_e32 v212, v149, v212
	v_mfma_f32_32x32x16_bf16 v[64:79], v[244:247], v[108:111], v[64:79]
	ds_read_b128 v[244:247], v200 offset:36864
	v_add_f32_e32 v211, v211, v212
	v_mov_b32_e32 v212, v211
	s_lshl_b32 s19, s18, 14
	v_add_u32_e32 v231, s19, v183
	s_waitcnt vmcnt(0)
	ds_write_b128 v231, v[140:143]
	v_add_u32_e32 v140, s19, v184
	ds_write_b128 v140, v[144:147]
	ds_write_b128 v185, v[136:139] offset:12288
	s_waitcnt lgkmcnt(6)
	v_mfma_f32_32x32x16_bf16 v[80:95], v[232:235], v[104:107], v[80:95]
	ds_read_b128 v[232:235], v200 offset:49152
	ds_write_b128 v185, v[132:135] offset:24576
	s_mov_b32 s18, 0xfffa0000
	ds_write_b128 v186, v[128:131] offset:12288
	v_add_co_u32_e32 v128, vcc, s18, v168
	s_mov_b32 s18, 0xfffc0000
	s_nop 0
	v_addc_co_u32_e32 v129, vcc, -1, v169, vcc
	v_add_co_u32_e32 v130, vcc, s18, v168
	s_movk_i32 s18, 0xe000
	s_nop 0
	v_addc_co_u32_e32 v131, vcc, -1, v169, vcc
	v_mfma_f32_32x32x16_bf16 v[64:79], v[236:239], v[104:107], v[64:79]
	ds_read_b128 v[236:239], v191 offset:36864
	global_load_dwordx4 v[140:143], v[128:129], off
	global_load_dwordx4 v[136:139], v[128:129], off offset:-256
	global_load_dwordx4 v[144:147], v[130:131], off
	global_load_dwordx4 v[132:135], v[130:131], off offset:-256
	v_add_co_u32_e32 v128, vcc, s18, v166
	s_nop 1
	v_addc_co_u32_e32 v129, vcc, -1, v167, vcc
	s_waitcnt lgkmcnt(8)
; __device__ __forceinline__ void partialSM(f32x16& p0, f32x16& p1, float& m_reg, float& mn, float& alpha) {
;   constexpr float C = SCALE * 1.4426950408889634f;
;   float pmax = p0[0];
; #pragma unroll
;   for (int r = 1; r < 16; ++r) pmax = fmaxf(pmax, p0[r]);
; #pragma unroll
;   for (int r = 0; r < 16; ++r) pmax = fmaxf(pmax, p1[r]);
;   { auto rr = __builtin_amdgcn_permlane32_swap(__float_as_uint(pmax), __float_as_uint(pmax), false, false);
;     pmax = fmaxf(__uint_as_float(rr[0]), __uint_as_float(rr[1])); }
;   if (__builtin_expect(__all(pmax - m_reg <= THR / SCALE), 1)) { mn = m_reg; alpha = 1.f; }
;   else { mn = fmaxf(m_reg, pmax); alpha = __builtin_amdgcn_exp2f((m_reg - mn) * C); m_reg = mn; }
;   float mnC = -mn * C;
; #pragma unroll
;   for (int r = 0; r < 16; ++r) p0[r] = fmaf(p0[r], C, mnC);
; #pragma unroll
;   for (int r = 0; r < 16; ++r) p1[r] = fmaf(p1[r], C, mnC);
; #pragma unroll
;   for (int r = 0; r < 16; ++r) p0[r] = __builtin_amdgcn_exp2f(p0[r]);
; }
; __device__ __forceinline__ void finishSM(f32x16& p0, f32x16& p1, float alpha, float& l_reg, bf16x8& pa0, bf16x8& pa1, bf16x8& pa2, bf16x8& pa3) {
; #pragma unroll
;   for (int r = 0; r < 16; ++r) p1[r] = __builtin_amdgcn_exp2f(p1[r]);
;   float ps = 0;
; #pragma unroll
;   for (int r = 0; r < 16; ++r) ps += p0[r];
; #pragma unroll
;   for (int r = 0; r < 16; ++r) ps += p1[r];
;   { auto rr = __builtin_amdgcn_permlane32_swap(__float_as_uint(ps), __float_as_uint(ps), false, false);
;     ps = __uint_as_float(rr[0]) + __uint_as_float(rr[1]); }
;   l_reg = l_reg * alpha + ps;
;     ...
;   PK4(p0, 0, pa0); PK4(p0, 8, pa1); PK4(p1, 0, pa2); PK4(p1, 8, pa3);
;     ...
; }
; template <int OFF> __device__ __forceinline__ s16x4 tr_read(int vb) {
;   s16x4 r; asm volatile("ds_read_b64_tr_b16 %0, %1 offset:%2" : "=&v"(r) : "v"(vb), "i"(OFF) : "memory"); return r;
; }
; template <int D0> __device__ __forceinline__ void pv_one(f32x16& od, int vb, bf16x8 pa0, bf16x8 pa1, bf16x8 pa2, bf16x8 pa3) {
;   const s16x4 l0 = tr_read<v_rd_off(D0, 0, 0)>(vb), h0 = tr_read<v_rd_off(D0, 0, 1)>(vb), l1 = tr_read<v_rd_off(D0, 1, 0)>(vb), h1 = tr_read<v_rd_off(D0, 1, 1)>(vb);
;   const s16x4 l2 = tr_read<v_rd_off(D0, 2, 0)>(vb), h2 = tr_read<v_rd_off(D0, 2, 1)>(vb), l3 = tr_read<v_rd_off(D0, 3, 0)>(vb), h3 = tr_read<v_rd_off(D0, 3, 1)>(vb);
;   asm volatile("s_waitcnt lgkmcnt(0)" ::: "memory"); SBAR();
	v_mfma_f32_32x32x16_bf16 v[80:95], v[240:243], v[100:103], v[80:95]
	ds_read_b128 v[240:243], v202 offset:49152
	global_load_dwordx4 v[128:131], v[128:129], off
	v_cvt_pk_bf16_f32 v158, v158, v159
	v_cvt_pk_bf16_f32 v159, v156, v157
	v_permlane32_swap_b32_e32 v211, v212
	v_cvt_pk_bf16_f32 v156, v162, v163
	v_cvt_pk_bf16_f32 v157, v160, v161
	v_mfma_f32_32x32x16_bf16 v[64:79], v[248:251], v[100:103], v[64:79]
	ds_read_b128 v[248:251], v182
	v_cvt_pk_bf16_f32 v160, v154, v155
	v_cvt_pk_bf16_f32 v161, v152, v153
	v_cvt_pk_bf16_f32 v162, v150, v151
	v_cvt_pk_bf16_f32 v163, v148, v149
	v_add_f32_e32 v211, v211, v212
	v_cvt_pk_bf16_f32 v148, v225, v228
	s_waitcnt lgkmcnt(5)
	v_mfma_f32_32x32x16_bf16 v[80:95], v[244:247], v[96:99], v[80:95]
	ds_read_b128 v[244:247], v198 offset:36864
	v_cvt_pk_bf16_f32 v149, v226, v229
	v_cvt_pk_bf16_f32 v150, v227, v230
	v_cvt_pk_bf16_f32 v151, v223, v224
	v_cvt_pk_bf16_f32 v152, v219, v221
	v_cvt_pk_bf16_f32 v153, v220, v222
	v_cvt_pk_bf16_f32 v154, v215, v217
	v_mfma_f32_32x32x16_bf16 v[64:79], v[232:235], v[96:99], v[64:79]
	ds_read_b128 v[232:235], v201 offset:49152
	v_cvt_pk_bf16_f32 v155, v216, v218
	v_fma_f32 v176, v209, v176, v211
	s_waitcnt lgkmcnt(2)
	v_mfma_f32_32x32x16_bf16 v[80:95], v[236:239], v[248:251], v[80:95]
	ds_read_b128 v[236:239], v181
	v_mfma_f32_32x32x16_bf16 v[64:79], v[240:243], v[248:251], v[64:79]
	ds_read_b128 v[240:243], v187 offset:36864
	ds_read_b128 v[248:251], v189 offset:49152
	s_waitcnt lgkmcnt(2)
	v_mfma_f32_32x32x16_bf16 v[80:95], v[244:247], v[236:239], v[80:95]
	ds_read_b128 v[244:247], v179
	v_mfma_f32_32x32x16_bf16 v[64:79], v[232:235], v[236:239], v[64:79]
	ds_read_b128 v[232:235], v188 offset:36864
	ds_read_b128 v[236:239], v190 offset:49152
	s_waitcnt lgkmcnt(2)
	v_mfma_f32_32x32x16_bf16 v[80:95], v[240:243], v[244:247], v[80:95]
	ds_read_b128 v[240:243], v177
	v_mfma_f32_32x32x16_bf16 v[64:79], v[248:251], v[244:247], v[64:79]
	s_waitcnt lgkmcnt(0)
	v_mfma_f32_32x32x16_bf16 v[80:95], v[232:235], v[240:243], v[80:95]
	v_mfma_f32_32x32x16_bf16 v[64:79], v[236:239], v[240:243], v[64:79]
	s_lshl_b32 s31, s30, 14
	v_add_u32_e32 v180, s31, v178
	ds_read_b64_tr_b16 v[232:233], v180 offset:0
	ds_read_b64_tr_b16 v[234:235], v180 offset:2048
	ds_read_b64_tr_b16 v[236:237], v180 offset:512
	ds_read_b64_tr_b16 v[238:239], v180 offset:2560
	ds_read_b64_tr_b16 v[240:241], v180 offset:1024
	ds_read_b64_tr_b16 v[242:243], v180 offset:3072
	ds_read_b64_tr_b16 v[248:249], v180 offset:1536
	ds_read_b64_tr_b16 v[250:251], v180 offset:3584
	ds_read_b64_tr_b16 v[244:245], v180 offset:4096
	ds_read_b64_tr_b16 v[246:247], v180 offset:6144
	s_nop 3
	v_max3_f32 v194, v80, v81, v82
	v_max3_f32 v195, v64, v65, v66
	v_max3_f32 v194, v194, v83, v84
	v_max3_f32 v195, v195, v67, v68
	v_max3_f32 v194, v194, v85, v86
	s_waitcnt lgkmcnt(6)
	v_mfma_f32_32x32x16_bf16 v[32:47], v[148:151], v[232:235], v[32:47]
	ds_read_b64_tr_b16 v[232:233], v180 offset:4608
	ds_read_b64_tr_b16 v[234:235], v180 offset:6656
	v_max3_f32 v195, v195, v69, v70
	v_max3_f32 v194, v194, v87, v88
	v_max3_f32 v195, v195, v71, v72
	v_max3_f32 v194, v194, v89, v90
	v_max3_f32 v195, v195, v73, v74
	v_mfma_f32_32x32x16_bf16 v[48:63], v[148:151], v[236:239], v[48:63]
	ds_read_b64_tr_b16 v[236:237], v180 offset:5120
	ds_read_b64_tr_b16 v[238:239], v180 offset:7168
	v_max3_f32 v194, v194, v91, v92
	v_max3_f32 v195, v195, v75, v76
	v_max3_f32 v194, v194, v93, v94
	v_max3_f32 v195, v195, v77, v78
	v_max3_f32 v194, v194, v95, v195
	s_waitcnt lgkmcnt(6)
	v_mfma_f32_32x32x16_bf16 v[16:31], v[148:151], v[240:243], v[16:31]
	ds_read_b64_tr_b16 v[240:241], v180 offset:5632
	ds_read_b64_tr_b16 v[242:243], v180 offset:7680
	v_max_f32_e32 v194, v194, v79
	v_mov_b32_e32 v195, v194
	s_nop 1
	v_permlane32_swap_b32_e32 v194, v195
	v_max_f32_e32 v194, v194, v195
	v_mfma_f32_32x32x16_bf16 v[0:15], v[148:151], v[248:251], v[0:15]
	ds_read_b64_tr_b16 v[248:249], v180 offset:8192
	ds_read_b64_tr_b16 v[250:251], v180 offset:10240
	v_sub_f32_e32 v195, v194, v210
	v_cmp_ge_f32_e32 vcc, s15, v195
	s_cmp_eq_u64 vcc, exec
	s_cselect_b64 s[40:41], -1, 0
	s_cbranch_scc1 .Lattn_fast1p
	v_max_f32_e32 v194, v210, v194
	v_sub_f32_e32 v195, v210, v194
	v_mul_f32_e32 v195, 0x3dd53b94, v195
	v_exp_f32_e32 v214, v195
	v_mov_b32_e32 v210, v194
	s_branch .Lattn_join1p

; #define SBAR() __builtin_amdgcn_sched_barrier(0)
; template <int OFF> __device__ __forceinline__ s16x4 tr_read(int vb) {
;   s16x4 r; asm volatile("ds_read_b64_tr_b16 %0, %1 offset:%2" : "=&v"(r) : "v"(vb), "i"(OFF) : "memory"); return r;
; }
; template <int D0> __device__ __forceinline__ void pv_one(f32x16& od, int vb, bf16x8 pa0, bf16x8 pa1, bf16x8 pa2, bf16x8 pa3) {
;   const s16x4 l0 = tr_read<v_rd_off(D0, 0, 0)>(vb), h0 = tr_read<v_rd_off(D0, 0, 1)>(vb), l1 = tr_read<v_rd_off(D0, 1, 0)>(vb), h1 = tr_read<v_rd_off(D0, 1, 1)>(vb);
;   const s16x4 l2 = tr_read<v_rd_off(D0, 2, 0)>(vb), h2 = tr_read<v_rd_off(D0, 2, 1)>(vb), l3 = tr_read<v_rd_off(D0, 3, 0)>(vb), h3 = tr_read<v_rd_off(D0, 3, 1)>(vb);
;   asm volatile("s_waitcnt lgkmcnt(0)" ::: "memory"); SBAR();
;     ...
;   od = __builtin_amdgcn_mfma_f32_32x32x16_bf16(pa0, PK(l0, h0), od, 0, 0, 0);
;   od = __builtin_amdgcn_mfma_f32_32x32x16_bf16(pa1, PK(l1, h1), od, 0, 0, 0);
;   od = __builtin_amdgcn_mfma_f32_32x32x16_bf16(pa2, PK(l2, h2), od, 0, 0, 0);
;   od = __builtin_amdgcn_mfma_f32_32x32x16_bf16(pa3, PK(l3, h3), od, 0, 0, 0);
;     ...
; }
; __device__ __forceinline__ void pv_d0(f32x16* o, int vb, bf16x8 pa0, bf16x8 pa1, bf16x8 pa2, bf16x8 pa3) {
;   pv_one<0>(o[0], vb, pa0, pa1, pa2, pa3); pv_one<1>(o[1], vb, pa0, pa1, pa2, pa3); pv_one<2>(o[2], vb, pa0, pa1, pa2, pa3); pv_one<3>(o[3], vb, pa0, pa1, pa2, pa3);
.Lattn_join1p:
	s_waitcnt lgkmcnt(6)
	v_mfma_f32_32x32x16_bf16 v[32:47], v[152:155], v[244:247], v[32:47]
	ds_read_b64_tr_b16 v[244:245], v180 offset:8704
	ds_read_b64_tr_b16 v[246:247], v180 offset:10752
	v_mul_f32_e32 v194, 0xbdd53b94, v210
	v_fmamk_f32 v225, v80, 0x3dd53b94, v194
	v_fmamk_f32 v228, v81, 0x3dd53b94, v194
	v_fmamk_f32 v226, v82, 0x3dd53b94, v194
	v_fmamk_f32 v229, v83, 0x3dd53b94, v194
	v_mfma_f32_32x32x16_bf16 v[48:63], v[152:155], v[232:235], v[48:63]
	ds_read_b64_tr_b16 v[232:233], v180 offset:9216
	ds_read_b64_tr_b16 v[234:235], v180 offset:11264
	v_fmamk_f32 v150, v76, 0x3dd53b94, v194
	v_fmamk_f32 v151, v77, 0x3dd53b94, v194
	v_fmamk_f32 v148, v78, 0x3dd53b94, v194
	v_fmamk_f32 v149, v79, 0x3dd53b94, v194
	v_fmamk_f32 v227, v84, 0x3dd53b94, v194
	s_waitcnt lgkmcnt(6)
	v_mfma_f32_32x32x16_bf16 v[16:31], v[152:155], v[236:239], v[16:31]
	ds_read_b64_tr_b16 v[236:237], v180 offset:9728
	ds_read_b64_tr_b16 v[238:239], v180 offset:11776
	v_fmamk_f32 v230, v85, 0x3dd53b94, v194
	v_fmamk_f32 v223, v86, 0x3dd53b94, v194
	v_fmamk_f32 v224, v87, 0x3dd53b94, v194
	v_mfma_f32_32x32x16_bf16 v[0:15], v[152:155], v[240:243], v[0:15]
	ds_read_b64_tr_b16 v[240:241], v180 offset:12288
	ds_read_b64_tr_b16 v[242:243], v180 offset:14336
	v_fmamk_f32 v154, v72, 0x3dd53b94, v194
	v_fmamk_f32 v155, v73, 0x3dd53b94, v194
	v_fmamk_f32 v152, v74, 0x3dd53b94, v194
	v_fmamk_f32 v153, v75, 0x3dd53b94, v194
	v_fmamk_f32 v219, v88, 0x3dd53b94, v194
	s_waitcnt lgkmcnt(6)
	v_mfma_f32_32x32x16_bf16 v[32:47], v[156:159], v[248:251], v[32:47]
	ds_read_b64_tr_b16 v[248:249], v180 offset:12800
	ds_read_b64_tr_b16 v[250:251], v180 offset:14848
	v_fmamk_f32 v221, v89, 0x3dd53b94, v194
	v_fmamk_f32 v220, v90, 0x3dd53b94, v194
	v_fmamk_f32 v222, v91, 0x3dd53b94, v194
	v_mfma_f32_32x32x16_bf16 v[48:63], v[156:159], v[244:247], v[48:63]
	ds_read_b64_tr_b16 v[244:245], v180 offset:13312
	ds_read_b64_tr_b16 v[246:247], v180 offset:15360
	s_waitcnt lgkmcnt(6)
	v_mfma_f32_32x32x16_bf16 v[16:31], v[156:159], v[232:235], v[16:31]
	ds_read_b64_tr_b16 v[232:233], v180 offset:13824
	ds_read_b64_tr_b16 v[234:235], v180 offset:15872
	v_mfma_f32_32x32x16_bf16 v[0:15], v[156:159], v[236:239], v[0:15]
	v_fmamk_f32 v158, v68, 0x3dd53b94, v194
	v_fmamk_f32 v159, v69, 0x3dd53b94, v194
	v_fmamk_f32 v156, v70, 0x3dd53b94, v194
	v_fmamk_f32 v157, v71, 0x3dd53b94, v194
	v_fmamk_f32 v215, v92, 0x3dd53b94, v194
	s_waitcnt lgkmcnt(0)
	s_barrier
	ds_read_b128 v[236:239], v199 offset:12288
	v_mfma_f32_32x32x16_bf16 v[32:47], v[160:163], v[240:243], v[32:47]
	ds_read_b128 v[240:243], v199 offset:24576
	v_fmamk_f32 v217, v93, 0x3dd53b94, v194
	v_fmamk_f32 v216, v94, 0x3dd53b94, v194
	v_fmamk_f32 v218, v95, 0x3dd53b94, v194
	v_mfma_f32_32x32x16_bf16 v[48:63], v[160:163], v[248:251], v[48:63]
	ds_read_b128 v[248:251], v205 offset:12288
	v_mfma_f32_32x32x16_bf16 v[16:31], v[160:163], v[244:247], v[16:31]
	ds_read_b128 v[244:247], v205 offset:24576
	v_mfma_f32_32x32x16_bf16 v[0:15], v[160:163], v[232:235], v[0:15]
	ds_read_b128 v[232:235], v206 offset:12288
	v_fmamk_f32 v162, v64, 0x3dd53b94, v194
	v_fmamk_f32 v163, v65, 0x3dd53b94, v194
	v_fmamk_f32 v160, v66, 0x3dd53b94, v194
	v_fmamk_f32 v161, v67, 0x3dd53b94, v194
	s_and_b64 vcc, exec, s[40:41]
	s_cbranch_vccnz .Lattn_skip_rs1p
	s_and_saveexec_b64 s[18:19], s[38:39]
	ds_write_b32 v175, v214 offset:128
	s_or_b64 exec, exec, s[18:19]
	s_waitcnt lgkmcnt(0)
	v_add_u32_e32 v194, v173, v164
	ds_read_b128 v[64:67], v194 offset:224
	ds_read_b128 v[68:71], v194 offset:192
	ds_read_b128 v[72:75], v194 offset:160
	ds_read_b128 v[76:79], v194 offset:128
	s_waitcnt lgkmcnt(0)
	v_pk_mul_f32 v[44:45], v[44:45], v[64:65]
	v_pk_mul_f32 v[46:47], v[46:47], v[66:67]
	v_pk_mul_f32 v[40:41], v[40:41], v[68:69]
	v_pk_mul_f32 v[42:43], v[42:43], v[70:71]
	v_pk_mul_f32 v[36:37], v[36:37], v[72:73]
	v_pk_mul_f32 v[38:39], v[38:39], v[74:75]
	v_pk_mul_f32 v[32:33], v[32:33], v[76:77]
	v_pk_mul_f32 v[34:35], v[34:35], v[78:79]
	v_pk_mul_f32 v[60:61], v[60:61], v[64:65]
	v_pk_mul_f32 v[62:63], v[62:63], v[66:67]
	v_pk_mul_f32 v[56:57], v[56:57], v[68:69]
	v_pk_mul_f32 v[58:59], v[58:59], v[70:71]
	v_pk_mul_f32 v[52:53], v[52:53], v[72:73]
	v_pk_mul_f32 v[54:55], v[54:55], v[74:75]
	v_pk_mul_f32 v[48:49], v[48:49], v[76:77]
	v_pk_mul_f32 v[50:51], v[50:51], v[78:79]
	v_pk_mul_f32 v[28:29], v[28:29], v[64:65]
	v_pk_mul_f32 v[30:31], v[30:31], v[66:67]
	v_pk_mul_f32 v[24:25], v[24:25], v[68:69]
	v_pk_mul_f32 v[26:27], v[26:27], v[70:71]
	v_pk_mul_f32 v[20:21], v[20:21], v[72:73]
	v_pk_mul_f32 v[22:23], v[22:23], v[74:75]
	v_pk_mul_f32 v[16:17], v[16:17], v[76:77]
	v_pk_mul_f32 v[18:19], v[18:19], v[78:79]
	v_pk_mul_f32 v[12:13], v[12:13], v[64:65]
	v_pk_mul_f32 v[14:15], v[14:15], v[66:67]
	v_pk_mul_f32 v[8:9], v[8:9], v[68:69]
	v_pk_mul_f32 v[10:11], v[10:11], v[70:71]
	v_pk_mul_f32 v[4:5], v[4:5], v[72:73]
	v_pk_mul_f32 v[6:7], v[6:7], v[74:75]
	v_pk_mul_f32 v[0:1], v[0:1], v[76:77]
	v_pk_mul_f32 v[2:3], v[2:3], v[78:79]

; __device__ __forceinline__ void partialSM(f32x16& p0, f32x16& p1, float& m_reg, float& mn, float& alpha) {
;   constexpr float C = SCALE * 1.4426950408889634f;
;   float pmax = p0[0];
; #pragma unroll
;   for (int r = 1; r < 16; ++r) pmax = fmaxf(pmax, p0[r]);
; #pragma unroll
;   for (int r = 0; r < 16; ++r) pmax = fmaxf(pmax, p1[r]);
;   { auto rr = __builtin_amdgcn_permlane32_swap(__float_as_uint(pmax), __float_as_uint(pmax), false, false);
;     pmax = fmaxf(__uint_as_float(rr[0]), __uint_as_float(rr[1])); }
;   if (__builtin_expect(__all(pmax - m_reg <= THR / SCALE), 1)) { mn = m_reg; alpha = 1.f; }
;   else { mn = fmaxf(m_reg, pmax); alpha = __builtin_amdgcn_exp2f((m_reg - mn) * C); m_reg = mn; }
;   float mnC = -mn * C;
; #pragma unroll
;   for (int r = 0; r < 16; ++r) p0[r] = fmaf(p0[r], C, mnC);
; #pragma unroll
;   for (int r = 0; r < 16; ++r) p1[r] = fmaf(p1[r], C, mnC);
; #pragma unroll
;   for (int r = 0; r < 16; ++r) p0[r] = __builtin_amdgcn_exp2f(p0[r]);
; }
; __device__ __forceinline__ void finishSM(f32x16& p0, f32x16& p1, float alpha, float& l_reg, bf16x8& pa0, bf16x8& pa1, bf16x8& pa2, bf16x8& pa3) {
; #pragma unroll
;   for (int r = 0; r < 16; ++r) p1[r] = __builtin_amdgcn_exp2f(p1[r]);
;   float ps = 0;
; #pragma unroll
;   for (int r = 0; r < 16; ++r) ps += p0[r];
; #pragma unroll
;   for (int r = 0; r < 16; ++r) ps += p1[r];
;   { auto rr = __builtin_amdgcn_permlane32_swap(__float_as_uint(ps), __float_as_uint(ps), false, false);
;     ps = __uint_as_float(rr[0]) + __uint_as_float(rr[1]); }
;   l_reg = l_reg * alpha + ps;
;     ...
;   PK4(p0, 0, pa0); PK4(p0, 8, pa1); PK4(p1, 0, pa2); PK4(p1, 8, pa3);
;     ...
; }
; template <int OFF> __device__ __forceinline__ s16x4 tr_read(int vb) {
;   s16x4 r; asm volatile("ds_read_b64_tr_b16 %0, %1 offset:%2" : "=&v"(r) : "v"(vb), "i"(OFF) : "memory"); return r;
; }
; template <int D0> __device__ __forceinline__ void pv_one(f32x16& od, int vb, bf16x8 pa0, bf16x8 pa1, bf16x8 pa2, bf16x8 pa3) {
;   const s16x4 l0 = tr_read<v_rd_off(D0, 0, 0)>(vb), h0 = tr_read<v_rd_off(D0, 0, 1)>(vb), l1 = tr_read<v_rd_off(D0, 1, 0)>(vb), h1 = tr_read<v_rd_off(D0, 1, 1)>(vb);
;   const s16x4 l2 = tr_read<v_rd_off(D0, 2, 0)>(vb), h2 = tr_read<v_rd_off(D0, 2, 1)>(vb), l3 = tr_read<v_rd_off(D0, 3, 0)>(vb), h3 = tr_read<v_rd_off(D0, 3, 1)>(vb);
;   asm volatile("s_waitcnt lgkmcnt(0)" ::: "memory"); SBAR();
.Lattn_noloadp:
	s_waitcnt lgkmcnt(3)
	v_mfma_f32_32x32x16_bf16 v[80:95], v[232:235], v[240:243], v[80:95]
	ds_read_b128 v[232:235], v179
	v_cvt_pk_bf16_f32 v158, v158, v159
	v_cvt_pk_bf16_f32 v159, v156, v157
	v_permlane32_swap_b32_e32 v211, v212
	v_cvt_pk_bf16_f32 v156, v162, v163
	v_cvt_pk_bf16_f32 v157, v160, v161
	v_cvt_pk_bf16_f32 v160, v154, v155
	v_mfma_f32_32x32x16_bf16 v[64:79], v[236:239], v[240:243], v[64:79]
	ds_read_b128 v[236:239], v188 offset:12288
	ds_read_b128 v[240:243], v190 offset:24576
	v_cvt_pk_bf16_f32 v161, v152, v153
	v_cvt_pk_bf16_f32 v162, v150, v151
	v_cvt_pk_bf16_f32 v163, v148, v149
	v_add_f32_e32 v211, v211, v212
	v_cvt_pk_bf16_f32 v148, v225, v228
	v_cvt_pk_bf16_f32 v149, v226, v229
	s_waitcnt lgkmcnt(2)
	v_mfma_f32_32x32x16_bf16 v[80:95], v[248:251], v[232:235], v[80:95]
	ds_read_b128 v[248:251], v177
	v_cvt_pk_bf16_f32 v150, v227, v230
	v_cvt_pk_bf16_f32 v151, v223, v224
	v_cvt_pk_bf16_f32 v152, v219, v221
	v_cvt_pk_bf16_f32 v153, v220, v222
	v_cvt_pk_bf16_f32 v154, v215, v217
	v_cvt_pk_bf16_f32 v155, v216, v218
	v_mfma_f32_32x32x16_bf16 v[64:79], v[244:247], v[232:235], v[64:79]
	v_fma_f32 v176, v214, v176, v211
	s_waitcnt lgkmcnt(0)
	v_mfma_f32_32x32x16_bf16 v[80:95], v[236:239], v[248:251], v[80:95]
	v_mfma_f32_32x32x16_bf16 v[64:79], v[240:243], v[248:251], v[64:79]
	v_lshl_add_u32 v231, s76, 14, v178
	ds_read_b64_tr_b16 v[232:233], v231 offset:0
	ds_read_b64_tr_b16 v[234:235], v231 offset:2048
	ds_read_b64_tr_b16 v[236:237], v231 offset:512
	ds_read_b64_tr_b16 v[238:239], v231 offset:2560
	ds_read_b64_tr_b16 v[240:241], v231 offset:1024
	ds_read_b64_tr_b16 v[242:243], v231 offset:3072
	ds_read_b64_tr_b16 v[248:249], v231 offset:1536
	ds_read_b64_tr_b16 v[250:251], v231 offset:3584
	ds_read_b64_tr_b16 v[244:245], v231 offset:4096
	ds_read_b64_tr_b16 v[246:247], v231 offset:6144
	s_nop 3
	s_mov_b64 s[100:101], 0x4000
	v_lshl_add_u64 v[166:167], v[166:167], 0, s[100:101]
	v_lshl_add_u64 v[168:169], v[168:169], 0, s[10:11]
	v_max3_f32 v194, v80, v81, v82
	v_max3_f32 v195, v64, v65, v66
	v_max3_f32 v194, v194, v83, v84
	s_waitcnt lgkmcnt(6)
	v_mfma_f32_32x32x16_bf16 v[32:47], v[148:151], v[232:235], v[32:47]
	ds_read_b64_tr_b16 v[232:233], v231 offset:4608
	ds_read_b64_tr_b16 v[234:235], v231 offset:6656
	v_max3_f32 v195, v195, v67, v68
	v_max3_f32 v194, v194, v85, v86
	v_max3_f32 v195, v195, v69, v70
	v_max3_f32 v194, v194, v87, v88
	v_max3_f32 v195, v195, v71, v72
	v_mfma_f32_32x32x16_bf16 v[48:63], v[148:151], v[236:239], v[48:63]
	ds_read_b64_tr_b16 v[236:237], v231 offset:5120
	ds_read_b64_tr_b16 v[238:239], v231 offset:7168
	v_max3_f32 v194, v194, v89, v90
	v_max3_f32 v195, v195, v73, v74
	v_max3_f32 v194, v194, v91, v92
	v_max3_f32 v195, v195, v75, v76
	v_max3_f32 v194, v194, v93, v94
	s_waitcnt lgkmcnt(6)
	v_mfma_f32_32x32x16_bf16 v[16:31], v[148:151], v[240:243], v[16:31]
	ds_read_b64_tr_b16 v[240:241], v231 offset:5632
	ds_read_b64_tr_b16 v[242:243], v231 offset:7680
	v_max3_f32 v195, v195, v77, v78
	v_max3_f32 v194, v194, v95, v195
	v_max_f32_e32 v194, v194, v79
	v_mov_b32_e32 v195, v194
	s_nop 1
	v_mfma_f32_32x32x16_bf16 v[0:15], v[148:151], v[248:251], v[0:15]
	ds_read_b64_tr_b16 v[248:249], v231 offset:8192
	ds_read_b64_tr_b16 v[250:251], v231 offset:10240
	v_permlane32_swap_b32_e32 v194, v195
	v_max_f32_e32 v194, v194, v195
	v_sub_f32_e32 v195, v194, v210
	v_cmp_ge_f32_e32 vcc, s15, v195
	s_waitcnt lgkmcnt(6)
	v_mfma_f32_32x32x16_bf16 v[32:47], v[152:155], v[244:247], v[32:47]
	ds_read_b64_tr_b16 v[244:245], v231 offset:8704
	ds_read_b64_tr_b16 v[246:247], v231 offset:10752
	s_cmp_eq_u64 vcc, exec
	s_cselect_b64 s[40:41], -1, 0
	s_cbranch_scc1 .Lattn_fast2p
	v_max_f32_e32 v194, v210, v194
	v_sub_f32_e32 v195, v210, v194
	v_mul_f32_e32 v195, 0x3dd53b94, v195
	v_exp_f32_e32 v213, v195
	v_mov_b32_e32 v210, v194
	s_branch .Lattn_join2p

; #define SBAR() __builtin_amdgcn_sched_barrier(0)
; template <int OFF> __device__ __forceinline__ s16x4 tr_read(int vb) {
;   s16x4 r; asm volatile("ds_read_b64_tr_b16 %0, %1 offset:%2" : "=&v"(r) : "v"(vb), "i"(OFF) : "memory"); return r;
; }
; template <int D0> __device__ __forceinline__ void pv_one(f32x16& od, int vb, bf16x8 pa0, bf16x8 pa1, bf16x8 pa2, bf16x8 pa3) {
;   const s16x4 l0 = tr_read<v_rd_off(D0, 0, 0)>(vb), h0 = tr_read<v_rd_off(D0, 0, 1)>(vb), l1 = tr_read<v_rd_off(D0, 1, 0)>(vb), h1 = tr_read<v_rd_off(D0, 1, 1)>(vb);
;   const s16x4 l2 = tr_read<v_rd_off(D0, 2, 0)>(vb), h2 = tr_read<v_rd_off(D0, 2, 1)>(vb), l3 = tr_read<v_rd_off(D0, 3, 0)>(vb), h3 = tr_read<v_rd_off(D0, 3, 1)>(vb);
;   asm volatile("s_waitcnt lgkmcnt(0)" ::: "memory"); SBAR();
;     ...
;   od = __builtin_amdgcn_mfma_f32_32x32x16_bf16(pa0, PK(l0, h0), od, 0, 0, 0);
;   od = __builtin_amdgcn_mfma_f32_32x32x16_bf16(pa1, PK(l1, h1), od, 0, 0, 0);
;   od = __builtin_amdgcn_mfma_f32_32x32x16_bf16(pa2, PK(l2, h2), od, 0, 0, 0);
;   od = __builtin_amdgcn_mfma_f32_32x32x16_bf16(pa3, PK(l3, h3), od, 0, 0, 0);
;     ...
; }
; __device__ __forceinline__ void pv_d0(f32x16* o, int vb, bf16x8 pa0, bf16x8 pa1, bf16x8 pa2, bf16x8 pa3) {
;   pv_one<0>(o[0], vb, pa0, pa1, pa2, pa3); pv_one<1>(o[1], vb, pa0, pa1, pa2, pa3); pv_one<2>(o[2], vb, pa0, pa1, pa2, pa3); pv_one<3>(o[3], vb, pa0, pa1, pa2, pa3);
.Lattn_join2p:
	v_mul_f32_e32 v194, 0xbdd53b94, v210
	s_sub_i32 s100, s30, 1
	s_cmp_eq_u32 s30, 0
	s_cselect_b32 s100, 2, s100
	s_add_i32 s101, s30, 1
	s_cmp_lg_u32 s30, 2
	s_cselect_b32 s101, s101, 0
	s_movk_i32 s34, 0x6000
	v_mfma_f32_32x32x16_bf16 v[48:63], v[152:155], v[232:235], v[48:63]
	ds_read_b64_tr_b16 v[232:233], v231 offset:9216
	ds_read_b64_tr_b16 v[234:235], v231 offset:11264
	v_fmamk_f32 v225, v80, 0x3dd53b94, v194
	v_fmamk_f32 v228, v81, 0x3dd53b94, v194
	v_fmamk_f32 v226, v82, 0x3dd53b94, v194
	v_fmamk_f32 v229, v83, 0x3dd53b94, v194
	v_fmamk_f32 v150, v76, 0x3dd53b94, v194
	s_waitcnt lgkmcnt(6)
	v_mfma_f32_32x32x16_bf16 v[16:31], v[152:155], v[236:239], v[16:31]
	ds_read_b64_tr_b16 v[236:237], v231 offset:9728
	ds_read_b64_tr_b16 v[238:239], v231 offset:11776
	v_fmamk_f32 v151, v77, 0x3dd53b94, v194
	v_fmamk_f32 v148, v78, 0x3dd53b94, v194
	v_fmamk_f32 v149, v79, 0x3dd53b94, v194
	v_fmamk_f32 v227, v84, 0x3dd53b94, v194
	v_fmamk_f32 v230, v85, 0x3dd53b94, v194
	v_mfma_f32_32x32x16_bf16 v[0:15], v[152:155], v[240:243], v[0:15]
	ds_read_b64_tr_b16 v[240:241], v231 offset:12288
	ds_read_b64_tr_b16 v[242:243], v231 offset:14336
	v_fmamk_f32 v223, v86, 0x3dd53b94, v194
	v_fmamk_f32 v224, v87, 0x3dd53b94, v194
	v_fmamk_f32 v154, v72, 0x3dd53b94, v194
	v_fmamk_f32 v155, v73, 0x3dd53b94, v194
	v_fmamk_f32 v152, v74, 0x3dd53b94, v194
	s_waitcnt lgkmcnt(6)
	v_mfma_f32_32x32x16_bf16 v[32:47], v[156:159], v[248:251], v[32:47]
	ds_read_b64_tr_b16 v[248:249], v231 offset:12800
	ds_read_b64_tr_b16 v[250:251], v231 offset:14848
	v_fmamk_f32 v153, v75, 0x3dd53b94, v194
	v_fmamk_f32 v219, v88, 0x3dd53b94, v194
	v_fmamk_f32 v221, v89, 0x3dd53b94, v194
	v_fmamk_f32 v220, v90, 0x3dd53b94, v194
	v_fmamk_f32 v222, v91, 0x3dd53b94, v194
	v_mfma_f32_32x32x16_bf16 v[48:63], v[156:159], v[244:247], v[48:63]
	ds_read_b64_tr_b16 v[244:245], v231 offset:13312
	ds_read_b64_tr_b16 v[246:247], v231 offset:15360
	s_waitcnt lgkmcnt(6)
	v_mfma_f32_32x32x16_bf16 v[16:31], v[156:159], v[232:235], v[16:31]
	ds_read_b64_tr_b16 v[232:233], v231 offset:13824
	ds_read_b64_tr_b16 v[234:235], v231 offset:15872
	v_mfma_f32_32x32x16_bf16 v[0:15], v[156:159], v[236:239], v[0:15]
	v_fmamk_f32 v158, v68, 0x3dd53b94, v194
	v_fmamk_f32 v159, v69, 0x3dd53b94, v194
	v_fmamk_f32 v156, v70, 0x3dd53b94, v194
	v_fmamk_f32 v157, v71, 0x3dd53b94, v194
	v_fmamk_f32 v215, v92, 0x3dd53b94, v194
	s_waitcnt lgkmcnt(0)
	s_barrier
	ds_read_b128 v[236:239], v199 offset:36864
	v_mfma_f32_32x32x16_bf16 v[32:47], v[160:163], v[240:243], v[32:47]
	ds_read_b128 v[240:243], v199 offset:49152
	v_fmamk_f32 v217, v93, 0x3dd53b94, v194
	v_fmamk_f32 v216, v94, 0x3dd53b94, v194
	v_fmamk_f32 v218, v95, 0x3dd53b94, v194
	v_mfma_f32_32x32x16_bf16 v[48:63], v[160:163], v[248:251], v[48:63]
	ds_read_b128 v[248:251], v205 offset:36864
	v_mfma_f32_32x32x16_bf16 v[16:31], v[160:163], v[244:247], v[16:31]
	ds_read_b128 v[244:247], v205 offset:49152
	v_mfma_f32_32x32x16_bf16 v[0:15], v[160:163], v[232:235], v[0:15]
	ds_read_b128 v[232:235], v206 offset:36864
	v_fmamk_f32 v162, v64, 0x3dd53b94, v194
	v_fmamk_f32 v163, v65, 0x3dd53b94, v194
	v_fmamk_f32 v160, v66, 0x3dd53b94, v194
	v_fmamk_f32 v161, v67, 0x3dd53b94, v194
	s_and_b64 vcc, exec, s[40:41]
	s_cbranch_vccnz .Lattn_skip_rs2p
	s_and_saveexec_b64 s[18:19], s[38:39]
	ds_write_b32 v175, v213 offset:128
	s_or_b64 exec, exec, s[18:19]
	s_waitcnt lgkmcnt(0)
	v_add_u32_e32 v194, v173, v164
	ds_read_b128 v[64:67], v194 offset:224
	ds_read_b128 v[68:71], v194 offset:192
	ds_read_b128 v[72:75], v194 offset:160
	ds_read_b128 v[76:79], v194 offset:128
	s_waitcnt lgkmcnt(0)
	v_pk_mul_f32 v[44:45], v[44:45], v[64:65]
	v_pk_mul_f32 v[46:47], v[46:47], v[66:67]
	v_pk_mul_f32 v[40:41], v[40:41], v[68:69]
	v_pk_mul_f32 v[42:43], v[42:43], v[70:71]
	v_pk_mul_f32 v[36:37], v[36:37], v[72:73]
	v_pk_mul_f32 v[38:39], v[38:39], v[74:75]
	v_pk_mul_f32 v[32:33], v[32:33], v[76:77]
	v_pk_mul_f32 v[34:35], v[34:35], v[78:79]
	v_pk_mul_f32 v[60:61], v[60:61], v[64:65]
	v_pk_mul_f32 v[62:63], v[62:63], v[66:67]
	v_pk_mul_f32 v[56:57], v[56:57], v[68:69]
	v_pk_mul_f32 v[58:59], v[58:59], v[70:71]
	v_pk_mul_f32 v[52:53], v[52:53], v[72:73]
	v_pk_mul_f32 v[54:55], v[54:55], v[74:75]
	v_pk_mul_f32 v[48:49], v[48:49], v[76:77]
	v_pk_mul_f32 v[50:51], v[50:51], v[78:79]
	v_pk_mul_f32 v[28:29], v[28:29], v[64:65]
	v_pk_mul_f32 v[30:31], v[30:31], v[66:67]
	v_pk_mul_f32 v[24:25], v[24:25], v[68:69]
	v_pk_mul_f32 v[26:27], v[26:27], v[70:71]
	v_pk_mul_f32 v[20:21], v[20:21], v[72:73]
	v_pk_mul_f32 v[22:23], v[22:23], v[74:75]
	v_pk_mul_f32 v[16:17], v[16:17], v[76:77]
	v_pk_mul_f32 v[18:19], v[18:19], v[78:79]
	v_pk_mul_f32 v[12:13], v[12:13], v[64:65]
	v_pk_mul_f32 v[14:15], v[14:15], v[66:67]
	v_pk_mul_f32 v[8:9], v[8:9], v[68:69]
	v_pk_mul_f32 v[10:11], v[10:11], v[70:71]
	v_pk_mul_f32 v[4:5], v[4:5], v[72:73]
	v_pk_mul_f32 v[6:7], v[6:7], v[74:75]
	v_pk_mul_f32 v[0:1], v[0:1], v[76:77]
	v_pk_mul_f32 v[2:3], v[2:3], v[78:79]

; __device__ __forceinline__ void finishSM(f32x16& p0, f32x16& p1, float alpha, float& l_reg, bf16x8& pa0, bf16x8& pa1, bf16x8& pa2, bf16x8& pa3) {
; #pragma unroll
;   for (int r = 0; r < 16; ++r) p1[r] = __builtin_amdgcn_exp2f(p1[r]);
;   float ps = 0;
; #pragma unroll
;   for (int r = 0; r < 16; ++r) ps += p0[r];
; #pragma unroll
;   for (int r = 0; r < 16; ++r) ps += p1[r];
;   { auto rr = __builtin_amdgcn_permlane32_swap(__float_as_uint(ps), __float_as_uint(ps), false, false);
;     ps = __uint_as_float(rr[0]) + __uint_as_float(rr[1]); }
;   l_reg = l_reg * alpha + ps;
;     ...
;   PK4(p0, 0, pa0); PK4(p0, 8, pa1); PK4(p1, 0, pa2); PK4(p1, 8, pa3);
;     ...
; }
; __device__ __forceinline__ void qkt(f32x16& p0, f32x16& p1, const char* Ks, const bf16x8* qr, const char* qrl, int r32, int hi) {
;   p0 = f32x16{}; p1 = f32x16{};
; #pragma unroll
;   for (int d0 = 0; d0 < 8; ++d0) { int cb = (d0 * 16 + hi * 8) * 2;
;     bf16x8 b0 = *reinterpret_cast<const bf16x8*>(Ks + KSWZ(r32, cb));
;     bf16x8 b1 = *reinterpret_cast<const bf16x8*>(Ks + KSWZ(32 + r32, cb));
;     p0 = __builtin_amdgcn_mfma_f32_32x32x16_bf16(b0, qr[d0], p0, 0, 0, 0);
;     p1 = __builtin_amdgcn_mfma_f32_32x32x16_bf16(b1, qr[d0], p1, 0, 0, 0); }
; #pragma unroll
;   for (int d0 = 8; d0 < 12; ++d0) { int cb = (d0 * 16 + hi * 8) * 2;
;     bf16x8 b0 = *reinterpret_cast<const bf16x8*>(Ks + KSWZ(r32, cb));
;     bf16x8 b1 = *reinterpret_cast<const bf16x8*>(Ks + KSWZ(32 + r32, cb));
;     bf16x8 qf = *reinterpret_cast<const bf16x8*>(qrl + (((2 * (d0 - 8) + hi) ^ ((r32 >> 1) & 7)) << 4));
;     p0 = __builtin_amdgcn_mfma_f32_32x32x16_bf16(b0, qf, p0, 0, 0, 0);
;     p1 = __builtin_amdgcn_mfma_f32_32x32x16_bf16(b1, qf, p1, 0, 0, 0); }
; }
.Lattn_steady:
	v_exp_f32_e32 v225, v225
	v_exp_f32_e32 v228, v228
	v_exp_f32_e32 v226, v226
	v_add_f32_e32 v211, v225, v228
	s_waitcnt lgkmcnt(3)
	v_mfma_f32_32x32x16_bf16 v[80:95], v[236:239], v[124:127], 0
	ds_read_b128 v[236:239], v206 offset:49152
	v_exp_f32_e32 v229, v229
	v_add_f32_e32 v211, v226, v211
	v_exp_f32_e32 v227, v227
	v_add_f32_e32 v211, v229, v211
	v_mfma_f32_32x32x16_bf16 v[64:79], v[240:243], v[124:127], 0
	ds_read_b128 v[240:243], v208 offset:36864
	v_exp_f32_e32 v230, v230
	v_add_f32_e32 v211, v227, v211
	v_exp_f32_e32 v223, v223
	v_add_f32_e32 v211, v230, v211
	s_waitcnt lgkmcnt(3)
	v_mfma_f32_32x32x16_bf16 v[80:95], v[248:251], v[120:123], v[80:95]
	ds_read_b128 v[248:251], v208 offset:49152
	v_exp_f32_e32 v224, v224
	v_add_f32_e32 v211, v223, v211
	v_exp_f32_e32 v219, v219
	v_add_f32_e32 v211, v224, v211
	v_mfma_f32_32x32x16_bf16 v[64:79], v[244:247], v[120:123], v[64:79]
	ds_read_b128 v[244:247], v207 offset:36864
	v_exp_f32_e32 v221, v221
	v_add_f32_e32 v211, v219, v211
	v_exp_f32_e32 v220, v220
	v_add_f32_e32 v211, v221, v211
	s_waitcnt lgkmcnt(3)
	v_mfma_f32_32x32x16_bf16 v[80:95], v[232:235], v[116:119], v[80:95]
	ds_read_b128 v[232:235], v207 offset:49152
	v_exp_f32_e32 v222, v222
	v_add_f32_e32 v211, v220, v211
	v_exp_f32_e32 v215, v215
	v_add_f32_e32 v211, v222, v211
	v_mfma_f32_32x32x16_bf16 v[64:79], v[236:239], v[116:119], v[64:79]
	ds_read_b128 v[236:239], v204 offset:36864
	v_exp_f32_e32 v217, v217
	v_add_f32_e32 v211, v215, v211
	v_exp_f32_e32 v216, v216
	v_add_f32_e32 v211, v217, v211
	s_waitcnt lgkmcnt(3)
	v_mfma_f32_32x32x16_bf16 v[80:95], v[240:243], v[112:115], v[80:95]
	ds_read_b128 v[240:243], v204 offset:49152
	v_exp_f32_e32 v218, v218
	v_add_f32_e32 v211, v216, v211
	v_exp_f32_e32 v162, v162
	v_add_f32_e32 v211, v218, v211
	v_mfma_f32_32x32x16_bf16 v[64:79], v[248:251], v[112:115], v[64:79]
	ds_read_b128 v[248:251], v203 offset:36864
	v_exp_f32_e32 v163, v163
	v_exp_f32_e32 v160, v160
	v_exp_f32_e32 v161, v161
	s_waitcnt lgkmcnt(3)
	v_mfma_f32_32x32x16_bf16 v[80:95], v[244:247], v[108:111], v[80:95]
	ds_read_b128 v[244:247], v203 offset:49152
	v_exp_f32_e32 v158, v158
	v_exp_f32_e32 v159, v159
	v_exp_f32_e32 v156, v156
	v_mfma_f32_32x32x16_bf16 v[64:79], v[232:235], v[108:111], v[64:79]
	ds_read_b128 v[232:235], v200 offset:36864
	v_exp_f32_e32 v157, v157
	v_exp_f32_e32 v154, v154
	v_exp_f32_e32 v155, v155
	s_waitcnt lgkmcnt(3)
	v_mfma_f32_32x32x16_bf16 v[80:95], v[236:239], v[104:107], v[80:95]
	ds_read_b128 v[236:239], v200 offset:49152
	v_exp_f32_e32 v152, v152
	v_exp_f32_e32 v153, v153
	v_exp_f32_e32 v150, v150
	v_mfma_f32_32x32x16_bf16 v[64:79], v[240:243], v[104:107], v[64:79]
	ds_read_b128 v[240:243], v191 offset:36864
	v_exp_f32_e32 v151, v151
	v_exp_f32_e32 v148, v148
	v_exp_f32_e32 v149, v149
	s_waitcnt lgkmcnt(3)
	v_mfma_f32_32x32x16_bf16 v[80:95], v[248:251], v[100:103], v[80:95]
	ds_read_b128 v[248:251], v202 offset:49152
	v_add_f32_e32 v212, v162, v163
	v_add_f32_e32 v212, v160, v212
	v_add_f32_e32 v212, v161, v212
	v_add_f32_e32 v212, v158, v212
	v_add_f32_e32 v212, v159, v212
	v_add_f32_e32 v212, v156, v212
	v_mfma_f32_32x32x16_bf16 v[64:79], v[244:247], v[100:103], v[64:79]
	ds_read_b128 v[244:247], v182
	v_add_f32_e32 v212, v157, v212
	v_add_f32_e32 v212, v154, v212
	v_add_f32_e32 v212, v155, v212
	v_add_f32_e32 v212, v152, v212
	v_add_f32_e32 v212, v153, v212
	v_add_f32_e32 v212, v150, v212
	s_waitcnt lgkmcnt(3)
	v_mfma_f32_32x32x16_bf16 v[80:95], v[232:235], v[96:99], v[80:95]
	ds_read_b128 v[232:235], v198 offset:36864
	v_add_f32_e32 v212, v151, v212
	v_add_f32_e32 v212, v148, v212
	v_add_f32_e32 v212, v149, v212
	v_add_f32_e32 v211, v211, v212
	v_mov_b32_e32 v212, v211
	s_lshl_b32 s19, s18, 14
	v_add_u32_e32 v231, s19, v183
	s_waitcnt vmcnt(0)
	v_mfma_f32_32x32x16_bf16 v[64:79], v[236:239], v[96:99], v[64:79]
	ds_read_b128 v[236:239], v201 offset:49152
	ds_write_b128 v231, v[140:143]
	v_add_u32_e32 v140, s19, v184
	ds_write_b128 v140, v[144:147]
	ds_write_b128 v185, v[136:139] offset:12288
	ds_write_b128 v185, v[132:135] offset:24576
	s_mov_b32 s18, 0xfffa0000
	ds_write_b128 v186, v[128:131] offset:12288
	v_add_co_u32_e32 v128, vcc, s18, v168
	s_mov_b32 s18, 0xfffc0000
	s_nop 0
	s_waitcnt lgkmcnt(7)
; __device__ __forceinline__ void partialSM(f32x16& p0, f32x16& p1, float& m_reg, float& mn, float& alpha) {
;   constexpr float C = SCALE * 1.4426950408889634f;
;   float pmax = p0[0];
; #pragma unroll
;   for (int r = 1; r < 16; ++r) pmax = fmaxf(pmax, p0[r]);
; #pragma unroll
;   for (int r = 0; r < 16; ++r) pmax = fmaxf(pmax, p1[r]);
;   { auto rr = __builtin_amdgcn_permlane32_swap(__float_as_uint(pmax), __float_as_uint(pmax), false, false);
;     pmax = fmaxf(__uint_as_float(rr[0]), __uint_as_float(rr[1])); }
;   if (__builtin_expect(__all(pmax - m_reg <= THR / SCALE), 1)) { mn = m_reg; alpha = 1.f; }
;   else { mn = fmaxf(m_reg, pmax); alpha = __builtin_amdgcn_exp2f((m_reg - mn) * C); m_reg = mn; }
;   float mnC = -mn * C;
; #pragma unroll
;   for (int r = 0; r < 16; ++r) p0[r] = fmaf(p0[r], C, mnC);
; #pragma unroll
;   for (int r = 0; r < 16; ++r) p1[r] = fmaf(p1[r], C, mnC);
; #pragma unroll
;   for (int r = 0; r < 16; ++r) p0[r] = __builtin_amdgcn_exp2f(p0[r]);
; }
; __device__ __forceinline__ void finishSM(f32x16& p0, f32x16& p1, float alpha, float& l_reg, bf16x8& pa0, bf16x8& pa1, bf16x8& pa2, bf16x8& pa3) {
; #pragma unroll
;   for (int r = 0; r < 16; ++r) p1[r] = __builtin_amdgcn_exp2f(p1[r]);
;   float ps = 0;
; #pragma unroll
;   for (int r = 0; r < 16; ++r) ps += p0[r];
; #pragma unroll
;   for (int r = 0; r < 16; ++r) ps += p1[r];
;   { auto rr = __builtin_amdgcn_permlane32_swap(__float_as_uint(ps), __float_as_uint(ps), false, false);
;     ps = __uint_as_float(rr[0]) + __uint_as_float(rr[1]); }
;   l_reg = l_reg * alpha + ps;
;     ...
;   PK4(p0, 0, pa0); PK4(p0, 8, pa1); PK4(p1, 0, pa2); PK4(p1, 8, pa3);
;     ...
; }
; template <int OFF> __device__ __forceinline__ s16x4 tr_read(int vb) {
;   s16x4 r; asm volatile("ds_read_b64_tr_b16 %0, %1 offset:%2" : "=&v"(r) : "v"(vb), "i"(OFF) : "memory"); return r;
; }
; template <int D0> __device__ __forceinline__ void pv_one(f32x16& od, int vb, bf16x8 pa0, bf16x8 pa1, bf16x8 pa2, bf16x8 pa3) {
;   const s16x4 l0 = tr_read<v_rd_off(D0, 0, 0)>(vb), h0 = tr_read<v_rd_off(D0, 0, 1)>(vb), l1 = tr_read<v_rd_off(D0, 1, 0)>(vb), h1 = tr_read<v_rd_off(D0, 1, 1)>(vb);
;   const s16x4 l2 = tr_read<v_rd_off(D0, 2, 0)>(vb), h2 = tr_read<v_rd_off(D0, 2, 1)>(vb), l3 = tr_read<v_rd_off(D0, 3, 0)>(vb), h3 = tr_read<v_rd_off(D0, 3, 1)>(vb);
;   asm volatile("s_waitcnt lgkmcnt(0)" ::: "memory"); SBAR();
	v_mfma_f32_32x32x16_bf16 v[80:95], v[240:243], v[244:247], v[80:95]
	ds_read_b128 v[240:243], v181
	v_addc_co_u32_e32 v129, vcc, -1, v169, vcc
	v_add_co_u32_e32 v130, vcc, s18, v168
	s_movk_i32 s18, 0xe000
	s_nop 0
	v_addc_co_u32_e32 v131, vcc, -1, v169, vcc
	global_load_dwordx4 v[140:143], v[128:129], off
	global_load_dwordx4 v[136:139], v[128:129], off offset:-256
	global_load_dwordx4 v[144:147], v[130:131], off
	v_mfma_f32_32x32x16_bf16 v[64:79], v[248:251], v[244:247], v[64:79]
	ds_read_b128 v[248:251], v187 offset:36864
	ds_read_b128 v[244:247], v189 offset:49152
	global_load_dwordx4 v[132:135], v[130:131], off offset:-256
	v_add_co_u32_e32 v128, vcc, s18, v166
	s_nop 1
	v_addc_co_u32_e32 v129, vcc, -1, v167, vcc
	global_load_dwordx4 v[128:131], v[128:129], off
	v_cvt_pk_bf16_f32 v158, v158, v159
	v_cvt_pk_bf16_f32 v159, v156, v157
	s_waitcnt lgkmcnt(2)
	v_mfma_f32_32x32x16_bf16 v[80:95], v[232:235], v[240:243], v[80:95]
	ds_read_b128 v[232:235], v179
	v_permlane32_swap_b32_e32 v211, v212
	v_cvt_pk_bf16_f32 v156, v162, v163
	v_cvt_pk_bf16_f32 v157, v160, v161
	v_cvt_pk_bf16_f32 v160, v154, v155
	v_cvt_pk_bf16_f32 v161, v152, v153
	v_cvt_pk_bf16_f32 v162, v150, v151
	v_mfma_f32_32x32x16_bf16 v[64:79], v[236:239], v[240:243], v[64:79]
	ds_read_b128 v[236:239], v188 offset:36864
	ds_read_b128 v[240:243], v190 offset:49152
	v_cvt_pk_bf16_f32 v163, v148, v149
	v_add_f32_e32 v211, v211, v212
	v_cvt_pk_bf16_f32 v148, v225, v228
	v_cvt_pk_bf16_f32 v149, v226, v229
	v_cvt_pk_bf16_f32 v150, v227, v230
	v_cvt_pk_bf16_f32 v151, v223, v224
	s_waitcnt lgkmcnt(2)
	v_mfma_f32_32x32x16_bf16 v[80:95], v[248:251], v[232:235], v[80:95]
	ds_read_b128 v[248:251], v177
	v_cvt_pk_bf16_f32 v152, v219, v221
	v_cvt_pk_bf16_f32 v153, v220, v222
	v_cvt_pk_bf16_f32 v154, v215, v217
	v_cvt_pk_bf16_f32 v155, v216, v218
	v_fma_f32 v176, v209, v176, v211
	v_mfma_f32_32x32x16_bf16 v[64:79], v[244:247], v[232:235], v[64:79]
	s_waitcnt lgkmcnt(0)
	v_mfma_f32_32x32x16_bf16 v[80:95], v[236:239], v[248:251], v[80:95]
	v_mfma_f32_32x32x16_bf16 v[64:79], v[240:243], v[248:251], v[64:79]
	s_lshl_b32 s31, s30, 14
	v_add_u32_e32 v180, s31, v178
	ds_read_b64_tr_b16 v[232:233], v180 offset:0
	ds_read_b64_tr_b16 v[234:235], v180 offset:2048
	ds_read_b64_tr_b16 v[236:237], v180 offset:512
	ds_read_b64_tr_b16 v[238:239], v180 offset:2560
	ds_read_b64_tr_b16 v[240:241], v180 offset:1024
	ds_read_b64_tr_b16 v[242:243], v180 offset:3072
	ds_read_b64_tr_b16 v[248:249], v180 offset:1536
	ds_read_b64_tr_b16 v[250:251], v180 offset:3584
	ds_read_b64_tr_b16 v[244:245], v180 offset:4096
	ds_read_b64_tr_b16 v[246:247], v180 offset:6144
	s_nop 3
	v_max3_f32 v194, v80, v81, v82
	v_max3_f32 v195, v64, v65, v66
	v_max3_f32 v194, v194, v83, v84
	v_max3_f32 v195, v195, v67, v68
	v_max3_f32 v194, v194, v85, v86
	s_waitcnt lgkmcnt(6)
	v_mfma_f32_32x32x16_bf16 v[32:47], v[148:151], v[232:235], v[32:47]
	ds_read_b64_tr_b16 v[232:233], v180 offset:4608
	ds_read_b64_tr_b16 v[234:235], v180 offset:6656
	v_max3_f32 v195, v195, v69, v70
	v_max3_f32 v194, v194, v87, v88
	v_max3_f32 v195, v195, v71, v72
	v_max3_f32 v194, v194, v89, v90
	v_max3_f32 v195, v195, v73, v74
	v_mfma_f32_32x32x16_bf16 v[48:63], v[148:151], v[236:239], v[48:63]
	ds_read_b64_tr_b16 v[236:237], v180 offset:5120
	ds_read_b64_tr_b16 v[238:239], v180 offset:7168
	v_max3_f32 v194, v194, v91, v92
	v_max3_f32 v195, v195, v75, v76
	v_max3_f32 v194, v194, v93, v94
	v_max3_f32 v195, v195, v77, v78
	v_max3_f32 v194, v194, v95, v195
	s_waitcnt lgkmcnt(6)
	v_mfma_f32_32x32x16_bf16 v[16:31], v[148:151], v[240:243], v[16:31]
	ds_read_b64_tr_b16 v[240:241], v180 offset:5632
	ds_read_b64_tr_b16 v[242:243], v180 offset:7680
	v_max_f32_e32 v194, v194, v79
	v_mov_b32_e32 v195, v194
	s_nop 1
	v_permlane32_swap_b32_e32 v194, v195
	v_max_f32_e32 v194, v194, v195
	v_mfma_f32_32x32x16_bf16 v[0:15], v[148:151], v[248:251], v[0:15]
	ds_read_b64_tr_b16 v[248:249], v180 offset:8192
	ds_read_b64_tr_b16 v[250:251], v180 offset:10240
	v_sub_f32_e32 v195, v194, v210
	v_cmp_ge_f32_e32 vcc, s15, v195
	s_cmp_eq_u64 vcc, exec
	s_cselect_b64 s[40:41], -1, 0
	s_cbranch_scc1 .Lattn_fast1
	v_max_f32_e32 v194, v210, v194
	v_sub_f32_e32 v195, v210, v194
	v_mul_f32_e32 v195, 0x3dd53b94, v195
	v_exp_f32_e32 v214, v195
	v_mov_b32_e32 v210, v194
	s_branch .Lattn_join1
